# mix2 chunk loop: barrier in front of the state-image write removed (image written after the next iteration's first barrier)
# baseline (speedup 1.0000x reference)
; #define LAS __attribute__((address_space(3)))
; __device__ __forceinline__ unsigned cvt_pk_bf16(float lo, float hi) { unsigned r; asm volatile("v_cvt_pk_bf16_f32 %0, %1, %2" : "=v"(r) : "v"(lo), "v"(hi)); return r; }
; __device__ void mix_sweep(const Params& P, LAS unsigned char* lds, int tok0, int pos0, int seqlen, int hd, int dir, bool state_only, bool final_pass,
;                           f32x4 (&Cacc)[9], float& m_state, float& aseg_sum, float lgam) {
;     ...
;     for (int ci = 0; ci < 8; ++ci) {
;         const int c = dir ? 7 - ci : ci; const int tok = tok0 + c * 128;
;         __syncthreads();
;         int tl = tid; asm volatile("" : "+v"(tl));
;         if (!state_only) {
; #pragma unroll
;             for (int it = 0; it < 4; ++it) { const int item = tl + 512 * it, r = item >> 4, ch = item & 15; t[0][it] = *(const u32x4*)(proj + (size_t)(tok + r) * NPROJ + qcol + 8 * ch); } }
; #pragma unroll
;     ...
; #pragma unroll
;             for (int it = 0; it < 4; ++it) { const int item = tl + 512 * it, r = item >> 4, ch = item & 15; *(LAS u32x4*)(img + offb(r, ch)) = t[which][it]; } }
;         if (ci < 7) { const int cn = dir ? 6 - ci : ci + 1; const int tokn = tok0 + cn * 128;
; #pragma unroll
;             for (int which = 1; which < 3; ++which) { const int cb = which == 1 ? kcol : vcolg;
; #pragma unroll
;                 for (int it = 0; it < 4; ++it) { const int item = tl + 512 * it, r = item >> 4, ch = item & 15; t[which][it] = *(const u32x4*)(proj + (size_t)(tokn + r) * NPROJ + cb + 8 * ch); } } }
;     ...
;         if (!state_only) {
;             __syncthreads();
; #pragma unroll
;             for (int nt = 0; nt < 8; ++nt) { u32x2 v; v.x = cvt_pk_bf16(Cacc[nt][0], Cacc[nt][1]); v.y = cvt_pk_bf16(Cacc[nt][2], Cacc[nt][3]);
;                 { LAUNDER_X16 *(LAS u32x2*)(lds + IMG_C + CWA(nt)) = v; } }
;             { u32x2 v; v.x = cvt_pk_bf16(Cacc[8][0], Cacc[8][1]); v.y = cvt_pk_bf16(Cacc[8][2], Cacc[8][3]); *(LAS u32x2*)(lds + IMG_CX + 32 * (16 * w + fr) + 8 * fg) = v; }
.LBB0_97:
	s_add_i32 s86, s86, -1
	s_add_i32 s83, s83, 1
	s_addk_i32 s87, 0x600
	s_add_i32 s88, s88, 8
	s_addk_i32 s7, 0x80
	s_cmp_lg_u32 s87, 0
	s_cbranch_scc0 .LBB0_74
.LBB0_98:
	s_xor_b32 s15, s7, 0x380
	s_and_b64 s[16:17], s[8:9], exec
	s_cselect_b32 s89, s7, s15
	v_mov_b32_e32 v92, v161
	s_add_i32 s89, s89, s79
	s_waitcnt lgkmcnt(0)
	s_barrier
	v_mov_b32_e32 v0, v179
	v_cvt_pk_bf16_f32 v72, v32, v33
	v_cvt_pk_bf16_f32 v73, v34, v35
	s_nop 0
	v_add_u32_e32 v0, v180, v0
	ds_write_b64 v0, v[72:73]
	v_mov_b32_e32 v0, v179
	v_cvt_pk_bf16_f32 v72, v28, v29
	v_cvt_pk_bf16_f32 v73, v30, v31
	s_nop 0
	v_xad_u32 v0, v0, 32, v180
	ds_write_b64 v0, v[72:73]
	v_mov_b32_e32 v0, v179
	v_cvt_pk_bf16_f32 v72, v24, v25
	v_cvt_pk_bf16_f32 v73, v26, v27
	s_nop 0
	v_xad_u32 v0, v0, 64, v180
	ds_write_b64 v0, v[72:73]
	v_mov_b32_e32 v0, v179
	v_cvt_pk_bf16_f32 v72, v20, v21
	v_cvt_pk_bf16_f32 v73, v22, v23
	s_nop 0
	v_xad_u32 v0, v0, s33, v180
	ds_write_b64 v0, v[72:73]
	v_mov_b32_e32 v0, v179
	v_cvt_pk_bf16_f32 v72, v16, v17
	v_cvt_pk_bf16_f32 v73, v18, v19
	s_nop 0
	v_xad_u32 v0, v0, s25, v180
	ds_write_b64 v0, v[72:73]
	v_mov_b32_e32 v0, v179
	v_cvt_pk_bf16_f32 v72, v12, v13
	v_cvt_pk_bf16_f32 v73, v14, v15
	s_nop 0
	v_xad_u32 v0, v0, s31, v180
	ds_write_b64 v0, v[72:73]
	v_mov_b32_e32 v0, v179
	v_cvt_pk_bf16_f32 v72, v8, v9
	v_cvt_pk_bf16_f32 v73, v10, v11
	s_nop 0
	v_xad_u32 v0, v0, s27, v180
	ds_write_b64 v0, v[72:73]
	v_mov_b32_e32 v0, v179
	v_cvt_pk_bf16_f32 v72, v4, v5
	v_cvt_pk_bf16_f32 v73, v6, v7
	s_nop 0
	v_xad_u32 v0, v0, s97, v180
	ds_write_b64 v0, v[72:73]
	v_cvt_pk_bf16_f32 v72, v36, v37
	v_cvt_pk_bf16_f32 v73, v38, v39
	s_nop 0
	ds_write_b64 v181, v[72:73]
	s_cmpk_eq_i32 s87, 0xfa00
	v_lshlrev_b32_e32 v0, 3, v92
	v_ashrrev_i32_e32 v72, 4, v92
	v_and_b32_e32 v0, 0x78, v0
	v_add_u32_e32 v74, s89, v72
	v_lshlrev_b32_e32 v0, 1, v0
	v_ashrrev_i32_e32 v75, 31, v74
	v_lshl_add_u64 v[88:89], s[36:37], 0, v[0:1]
	v_lshlrev_b64 v[74:75], 13, v[74:75]
	v_add_u32_e32 v73, 0x200, v92
	v_lshl_add_u64 v[74:75], v[88:89], 0, v[74:75]
	v_ashrrev_i32_e32 v73, 4, v73
	global_load_dwordx4 v[76:79], v[74:75], off
	v_add_u32_e32 v74, s89, v73
	v_ashrrev_i32_e32 v75, 31, v74
	v_lshlrev_b64 v[74:75], 13, v[74:75]
	v_lshl_add_u64 v[74:75], v[88:89], 0, v[74:75]
	global_load_dwordx4 v[80:83], v[74:75], off
	v_add_u32_e32 v74, 0x400, v92
	v_ashrrev_i32_e32 v74, 4, v74
	v_add_u32_e32 v75, 0x600, v92
	v_add_u32_e32 v84, s89, v74
	v_ashrrev_i32_e32 v75, 4, v75
	v_ashrrev_i32_e32 v85, 31, v84
	v_add_u32_e32 v90, s89, v75
	v_lshlrev_b64 v[84:85], 13, v[84:85]
	v_ashrrev_i32_e32 v91, 31, v90
	v_lshl_add_u64 v[84:85], v[88:89], 0, v[84:85]
	v_lshlrev_b64 v[90:91], 13, v[90:91]
	global_load_dwordx4 v[84:87], v[84:85], off
	v_lshl_add_u64 v[88:89], v[88:89], 0, v[90:91]
	global_load_dwordx4 v[88:91], v[88:89], off
	v_lshlrev_b32_e32 v94, 2, v72
	v_and_b32_e32 v92, 15, v92
	v_and_b32_e32 v94, 12, v94
	v_bfe_u32 v95, v72, 2, 2
	v_bitop3_b32 v94, v94, v92, v95 bitop3:0x36
	v_lshlrev_b32_e32 v96, 2, v73
	v_lshlrev_b32_e32 v93, 8, v72
	v_lshlrev_b32_e32 v94, 4, v94
	v_and_b32_e32 v96, 12, v96
	v_bfe_u32 v97, v73, 2, 2
	v_add3_u32 v95, s85, v94, v93
	v_bitop3_b32 v96, v96, v92, v97 bitop3:0x36
	v_lshlrev_b32_e32 v98, 2, v74
	s_waitcnt vmcnt(7)
	ds_write_b128 v95, v[56:59]
	v_lshlrev_b32_e32 v95, 8, v73
	v_lshlrev_b32_e32 v96, 4, v96
	v_and_b32_e32 v98, 12, v98
	v_bfe_u32 v99, v74, 2, 2
	v_add3_u32 v97, s85, v96, v95
	v_bitop3_b32 v98, v98, v92, v99 bitop3:0x36
	v_lshlrev_b32_e32 v100, 2, v75
	s_waitcnt vmcnt(6)
	ds_write_b128 v97, v[60:63]
	v_lshlrev_b32_e32 v97, 8, v74
	v_lshlrev_b32_e32 v98, 4, v98
	v_and_b32_e32 v100, 12, v100
	v_bfe_u32 v101, v75, 2, 2
	v_add3_u32 v99, s85, v98, v97
	v_bitop3_b32 v92, v100, v92, v101 bitop3:0x36
	s_waitcnt vmcnt(5)
	ds_write_b128 v99, v[64:67]
	v_lshlrev_b32_e32 v99, 8, v75
	v_lshlrev_b32_e32 v92, 4, v92
	v_add3_u32 v100, s85, v92, v99
	v_add3_u32 v93, 0, v94, v93
	v_add3_u32 v94, 0, v96, v95
	v_add3_u32 v95, 0, v98, v97
	v_add3_u32 v92, 0, v92, v99
	s_waitcnt vmcnt(4)
	ds_write_b128 v100, v[68:71]
	ds_write_b128 v93, v[40:43] offset:32768
	ds_write_b128 v94, v[44:47] offset:32768
	ds_write_b128 v95, v[48:51] offset:32768
	ds_write_b128 v92, v[52:55] offset:32768
	s_waitcnt vmcnt(3)
	ds_write_b128 v93, v[76:79]
	s_waitcnt vmcnt(2)
	ds_write_b128 v94, v[80:83]
	s_waitcnt vmcnt(1)
	ds_write_b128 v95, v[84:87]
	s_waitcnt vmcnt(0)
	ds_write_b128 v92, v[88:91]
	s_cbranch_scc1 .LBB0_100
	s_and_b64 s[16:17], s[8:9], exec
	s_cselect_b32 s15, s83, s86
	s_lshl_b32 s15, s15, 7
	s_add_i32 s15, s15, s79
	v_add_u32_e32 v40, s15, v72
	v_add_u32_e32 v42, s15, v73
	v_add_u32_e32 v50, s15, v74
	v_add_u32_e32 v52, s15, v75
	v_lshl_add_u64 v[56:57], s[22:23], 0, v[0:1]
	v_ashrrev_i32_e32 v41, 31, v40
	v_ashrrev_i32_e32 v43, 31, v42
	v_ashrrev_i32_e32 v51, 31, v50
	v_ashrrev_i32_e32 v53, 31, v52
	s_mov_b32 s15, s39
	v_lshlrev_b64 v[58:59], 13, v[40:41]
	v_lshl_add_u64 v[48:49], v[56:57], 0, s[38:39]
	v_lshlrev_b64 v[60:61], 13, v[42:43]
	v_lshlrev_b64 v[64:65], 13, v[50:51]
	v_lshlrev_b64 v[66:67], 13, v[52:53]
	v_lshl_add_u64 v[68:69], v[56:57], 0, s[14:15]
	v_lshl_add_u64 v[40:41], v[48:49], 0, v[58:59]
	v_lshl_add_u64 v[44:45], v[48:49], 0, v[60:61]
	v_lshl_add_u64 v[50:51], v[48:49], 0, v[64:65]
	v_lshl_add_u64 v[52:53], v[48:49], 0, v[66:67]
	v_lshl_add_u64 v[56:57], v[68:69], 0, v[58:59]
	v_lshl_add_u64 v[60:61], v[68:69], 0, v[60:61]
	v_lshl_add_u64 v[64:65], v[68:69], 0, v[64:65]
	v_lshl_add_u64 v[68:69], v[68:69], 0, v[66:67]
	global_load_dwordx4 v[40:43], v[40:41], off
	s_nop 0
	global_load_dwordx4 v[44:47], v[44:45], off
	s_nop 0
	global_load_dwordx4 v[48:51], v[50:51], off
	s_nop 0
	global_load_dwordx4 v[52:55], v[52:53], off
	s_nop 0
	global_load_dwordx4 v[56:59], v[56:57], off
	s_nop 0
	global_load_dwordx4 v[60:63], v[60:61], off
	s_nop 0
	global_load_dwordx4 v[64:67], v[64:65], off
	s_nop 0
	global_load_dwordx4 v[68:71], v[68:69], off
